# nt policy also on the read-once residual-stream loads (layer-0 mixer f32 x, mixer/FFN-down A' reads, final norm); on top of v47
# baseline (speedup 1.0000x reference)
.LBB0_1055:
	v_mbcnt_lo_u32_b32 v146, -1, 0
	v_mbcnt_hi_u32_b32 v146, -1, v146
	s_lshl_b32 s1, s1, 8
	v_bfe_u32 v245, v146, 4, 2
	v_lshl_or_b32 v98, v245, 3, s1
	s_lshl_b32 s1, s0, 7
	v_or_b32_e32 v196, s82, v98
	s_and_b32 s1, s1, 0xfffff800
	v_add_u32_e32 v98, s1, v196
	v_ashrrev_i32_e32 v99, 31, v98
	v_lshlrev_b64 v[98:99], 2, v[98:99]
	v_lshl_add_u64 v[208:209], s[14:15], 0, v[98:99]
	s_mov_b32 s96, 0xfffb8000
	s_mov_b32 s97, -1
	v_lshl_add_u64 v[186:187], v[208:209], 0, s[96:97]
	v_lshl_add_u64 v[210:211], s[16:17], 0, v[98:99]
	flat_load_dwordx4 v[110:113], v[208:209]
	flat_load_dwordx4 v[106:109], v[208:209] offset:16
	flat_load_dwordx4 v[102:105], v[210:211]
	flat_load_dwordx4 v[98:101], v[210:211] offset:16
	s_lshl_b32 s0, s0, 8
	s_add_i32 s0, s0, s72
	v_and_or_b32 v178, v146, 15, s0
	v_ashrrev_i32_e32 v197, 31, v196
	v_ashrrev_i32_e32 v179, 31, v178
	v_cndmask_b32_e64 v146, 0, 1, s[22:23]
	v_cmp_ne_u32_e64 s[8:9], 1, v146
	s_andn2_b64 vcc, exec, s[22:23]
	v_lshlrev_b64 v[212:213], 13, v[178:179]
	v_lshl_add_u64 v[188:189], v[196:197], 2, s[10:11]
	v_or_b32_e32 v200, 16, v178
	v_or_b32_e32 v198, 32, v178
	v_or_b32_e32 v194, 48, v178
	s_cbranch_vccnz .LBB0_1065
	v_lshl_add_u64 v[146:147], v[188:189], 0, v[212:213]
	v_ashrrev_i32_e32 v201, 31, v200
	global_load_dwordx4 v[174:177], v[146:147], off offset:16 nt
	global_load_dwordx4 v[170:173], v[146:147], off nt
	v_lshlrev_b64 v[146:147], 13, v[200:201]
	v_lshl_add_u64 v[146:147], v[188:189], 0, v[146:147]
	v_ashrrev_i32_e32 v199, 31, v198
	global_load_dwordx4 v[166:169], v[146:147], off offset:16 nt
	global_load_dwordx4 v[162:165], v[146:147], off nt
	v_lshlrev_b64 v[146:147], 13, v[198:199]
	v_lshl_add_u64 v[146:147], v[188:189], 0, v[146:147]
	v_ashrrev_i32_e32 v195, 31, v194
	global_load_dwordx4 v[158:161], v[146:147], off offset:16 nt
	global_load_dwordx4 v[154:157], v[146:147], off nt
	v_lshlrev_b64 v[146:147], 13, v[194:195]
	v_lshl_add_u64 v[146:147], v[188:189], 0, v[146:147]
	global_load_dwordx4 v[150:153], v[146:147], off offset:16 nt
	s_nop 0
	global_load_dwordx4 v[146:149], v[146:147], off nt
	v_lshlrev_b64 v[214:215], 12, v[178:179]
	v_lshl_add_u64 v[226:227], v[196:197], 1, s[12:13]
	s_cbranch_execnz .LBB0_1058
.LBB0_1057:
	v_ashrrev_i32_e32 v199, 31, v198
	s_waitcnt vmcnt(0)
	global_load_dwordx4 v[218:221], v[186:187], off
	global_load_dwordx4 v[222:225], v[186:187], off offset:16
	v_lshlrev_b64 v[154:155], 12, v[198:199]
	v_ashrrev_i32_e32 v201, 31, v200
	v_lshl_add_u64 v[154:155], v[226:227], 0, v[154:155]
	v_ashrrev_i32_e32 v195, 31, v194
	v_lshlrev_b64 v[150:151], 12, v[200:201]
	flat_load_dwordx4 v[158:161], v[154:155] nt
	v_lshlrev_b64 v[154:155], 12, v[194:195]
	v_lshl_add_u64 v[146:147], v[226:227], 0, v[214:215]
	v_lshl_add_u64 v[150:151], v[226:227], 0, v[150:151]
	v_lshl_add_u64 v[154:155], v[226:227], 0, v[154:155]
	flat_load_dwordx4 v[146:149], v[146:147] nt
	flat_load_dwordx4 v[150:153], v[150:151] nt
	flat_load_dwordx4 v[182:185], v[154:155] nt
	s_waitcnt vmcnt(0) lgkmcnt(0)
	v_lshlrev_b32_e32 v156, 16, v159
	v_and_b32_e32 v157, 0xffff0000, v159
	v_lshlrev_b32_e32 v154, 16, v158
	v_lshlrev_b32_e32 v170, 16, v146
	v_and_b32_e32 v171, 0xffff0000, v146
	v_lshlrev_b32_e32 v172, 16, v147
	v_and_b32_e32 v173, 0xffff0000, v147
	v_lshlrev_b32_e32 v174, 16, v148
	v_and_b32_e32 v175, 0xffff0000, v148
	v_lshlrev_b32_e32 v176, 16, v149
	v_and_b32_e32 v177, 0xffff0000, v149
	v_and_b32_e32 v155, 0xffff0000, v158
	v_lshlrev_b32_e32 v158, 16, v160
	v_and_b32_e32 v159, 0xffff0000, v160
	v_lshlrev_b32_e32 v160, 16, v161
	v_and_b32_e32 v161, 0xffff0000, v161
	s_waitcnt vmcnt(0) lgkmcnt(0)
	v_lshlrev_b32_e32 v162, 16, v150
	v_and_b32_e32 v163, 0xffff0000, v150
	v_lshlrev_b32_e32 v164, 16, v151
	v_and_b32_e32 v165, 0xffff0000, v151
	v_lshlrev_b32_e32 v166, 16, v152
	v_and_b32_e32 v167, 0xffff0000, v152
	v_lshlrev_b32_e32 v168, 16, v153
	v_and_b32_e32 v169, 0xffff0000, v153
	v_lshlrev_b32_e32 v146, 16, v182
	v_and_b32_e32 v147, 0xffff0000, v182
	v_lshlrev_b32_e32 v148, 16, v183
	v_and_b32_e32 v149, 0xffff0000, v183
	v_lshlrev_b32_e32 v150, 16, v184
	v_and_b32_e32 v151, 0xffff0000, v184
	v_lshlrev_b32_e32 v152, 16, v185
	v_and_b32_e32 v153, 0xffff0000, v185
	s_cmp_lt_u32 s68, 2
	s_cbranch_scc1 .Lxr2_0
	v_rcp_f32_e32 v218, v218
	v_rcp_f32_e32 v219, v219
	v_rcp_f32_e32 v220, v220
	v_rcp_f32_e32 v221, v221
	v_rcp_f32_e32 v222, v222
	v_rcp_f32_e32 v223, v223
	v_rcp_f32_e32 v224, v224
	v_rcp_f32_e32 v225, v225
	s_nop 0
	v_pk_mul_f32 v[146:147], v[146:147], v[218:219]
	v_pk_mul_f32 v[148:149], v[148:149], v[220:221]
	v_pk_mul_f32 v[150:151], v[150:151], v[222:223]
	v_pk_mul_f32 v[152:153], v[152:153], v[224:225]
	v_pk_mul_f32 v[154:155], v[154:155], v[218:219]
	v_pk_mul_f32 v[156:157], v[156:157], v[220:221]
	v_pk_mul_f32 v[158:159], v[158:159], v[222:223]
	v_pk_mul_f32 v[160:161], v[160:161], v[224:225]
	v_pk_mul_f32 v[162:163], v[162:163], v[218:219]
	v_pk_mul_f32 v[164:165], v[164:165], v[220:221]
	v_pk_mul_f32 v[166:167], v[166:167], v[222:223]
	v_pk_mul_f32 v[168:169], v[168:169], v[224:225]
	v_pk_mul_f32 v[170:171], v[170:171], v[218:219]
	v_pk_mul_f32 v[172:173], v[172:173], v[220:221]
	v_pk_mul_f32 v[174:175], v[174:175], v[222:223]
	v_pk_mul_f32 v[176:177], v[176:177], v[224:225]
.Lxr2_0:
.LBB0_1058:
	v_lshlrev_b64 v[216:217], 11, v[178:179]
	v_lshl_add_u64 v[182:183], v[216:217], 0, v[196:197]
	s_waitcnt vmcnt(0) lgkmcnt(0)
	v_pk_fma_f32 v[192:193], v[142:143], v[110:111], v[170:171]
	v_lshlrev_b64 v[142:143], 1, v[182:183]
	v_pk_fma_f32 v[190:191], v[144:145], v[112:113], v[172:173]
	v_pk_fma_f32 v[174:175], v[138:139], v[106:107], v[174:175]
	v_cvt_pk_bf16_f32 v138, v192, v193
	v_cvt_pk_bf16_f32 v139, v190, v191
	v_lshl_add_u64 v[144:145], s[12:13], 0, v[142:143]
	v_pk_fma_f32 v[176:177], v[140:141], v[108:109], v[176:177]
	v_cvt_pk_bf16_f32 v140, v174, v175
	v_lshl_add_u64 v[142:143], s[18:19], 0, v[142:143]
	v_cvt_pk_bf16_f32 v141, v176, v177
	v_lshlrev_b64 v[218:219], 11, v[200:201]
	v_pk_mul_f32 v[144:145], v[100:101], v[176:177]
	v_pk_mul_f32 v[138:139], v[102:103], v[192:193]
	v_pk_mul_f32 v[140:141], v[104:105], v[190:191]
	v_cvt_pk_bf16_f32 v138, v138, v139
	v_pk_mul_f32 v[170:171], v[98:99], v[174:175]
	v_cvt_pk_bf16_f32 v139, v140, v141
	v_pk_fma_f32 v[172:173], v[134:135], v[110:111], v[162:163]
	v_cvt_pk_bf16_f32 v140, v170, v171
	v_cvt_pk_bf16_f32 v141, v144, v145
	flat_store_dwordx4 v[142:143], v[138:141]
	v_pk_fma_f32 v[170:171], v[136:137], v[112:113], v[164:165]
	v_pk_fma_f32 v[166:167], v[130:131], v[106:107], v[166:167]
	v_lshl_add_u64 v[138:139], v[218:219], 0, v[196:197]
	v_lshlrev_b64 v[134:135], 1, v[138:139]
	v_cvt_pk_bf16_f32 v130, v172, v173
	v_cvt_pk_bf16_f32 v131, v170, v171
	v_lshl_add_u64 v[136:137], s[12:13], 0, v[134:135]
	v_pk_fma_f32 v[168:169], v[132:133], v[108:109], v[168:169]
	v_cvt_pk_bf16_f32 v132, v166, v167
	v_lshl_add_u64 v[134:135], s[18:19], 0, v[134:135]
	v_cvt_pk_bf16_f32 v133, v168, v169
	v_lshlrev_b64 v[220:221], 11, v[198:199]
	v_pk_mul_f32 v[136:137], v[100:101], v[168:169]
	v_pk_mul_f32 v[130:131], v[102:103], v[172:173]
	v_pk_mul_f32 v[132:133], v[104:105], v[170:171]
	v_cvt_pk_bf16_f32 v130, v130, v131
	v_pk_mul_f32 v[138:139], v[98:99], v[166:167]
	v_cvt_pk_bf16_f32 v131, v132, v133
	v_pk_fma_f32 v[164:165], v[126:127], v[110:111], v[154:155]
	v_cvt_pk_bf16_f32 v132, v138, v139
	v_cvt_pk_bf16_f32 v133, v136, v137
	flat_store_dwordx4 v[134:135], v[130:133]
	v_pk_fma_f32 v[162:163], v[128:129], v[112:113], v[156:157]
	v_pk_fma_f32 v[158:159], v[122:123], v[106:107], v[158:159]
	v_lshl_add_u64 v[130:131], v[220:221], 0, v[196:197]
	v_lshlrev_b64 v[126:127], 1, v[130:131]
	v_cvt_pk_bf16_f32 v122, v164, v165
	v_cvt_pk_bf16_f32 v123, v162, v163
	v_lshl_add_u64 v[128:129], s[12:13], 0, v[126:127]
	v_pk_fma_f32 v[156:157], v[124:125], v[108:109], v[160:161]
	v_cvt_pk_bf16_f32 v124, v158, v159
	v_lshl_add_u64 v[126:127], s[18:19], 0, v[126:127]
	v_cvt_pk_bf16_f32 v125, v156, v157
	v_lshlrev_b64 v[222:223], 11, v[194:195]
	v_pk_mul_f32 v[128:129], v[100:101], v[156:157]
	v_pk_mul_f32 v[122:123], v[102:103], v[164:165]
	v_pk_mul_f32 v[124:125], v[104:105], v[162:163]
	v_cvt_pk_bf16_f32 v122, v122, v123
	v_pk_mul_f32 v[130:131], v[98:99], v[158:159]
	v_cvt_pk_bf16_f32 v123, v124, v125
	v_pk_fma_f32 v[154:155], v[118:119], v[110:111], v[146:147]
	v_cvt_pk_bf16_f32 v124, v130, v131
	v_cvt_pk_bf16_f32 v125, v128, v129
	flat_store_dwordx4 v[126:127], v[122:125]
	v_pk_fma_f32 v[146:147], v[116:117], v[108:109], v[152:153]
	v_add_u32_e32 v152, 0x80, v178
	v_lshl_add_u64 v[122:123], v[222:223], 0, v[196:197]
	v_lshlrev_b64 v[118:119], 1, v[122:123]
	v_pk_fma_f32 v[148:149], v[120:121], v[112:113], v[148:149]
	v_pk_fma_f32 v[150:151], v[114:115], v[106:107], v[150:151]
	v_cvt_pk_bf16_f32 v114, v154, v155
	v_cvt_pk_bf16_f32 v115, v148, v149
	v_lshl_add_u64 v[120:121], s[12:13], 0, v[118:119]
	v_cvt_pk_bf16_f32 v116, v150, v151
	v_cvt_pk_bf16_f32 v117, v146, v147
	v_ashrrev_i32_e32 v153, 31, v152
	v_lshl_add_u64 v[118:119], s[18:19], 0, v[118:119]
	s_and_b64 vcc, exec, s[8:9]
	v_pk_mul_f32 v[116:117], v[104:105], v[148:149]
	v_pk_mul_f32 v[114:115], v[102:103], v[154:155]
	v_lshlrev_b64 v[224:225], 13, v[152:153]
	v_add_u32_e32 v206, 0x90, v178
	v_add_u32_e32 v204, 0xa0, v178
	v_add_u32_e32 v202, 0xb0, v178
	v_pk_mul_f32 v[120:121], v[100:101], v[146:147]
	v_pk_mul_f32 v[122:123], v[98:99], v[150:151]
	v_cvt_pk_bf16_f32 v114, v114, v115
	v_cvt_pk_bf16_f32 v115, v116, v117
	s_nop 0
	v_cvt_pk_bf16_f32 v116, v122, v123
	v_cvt_pk_bf16_f32 v117, v120, v121
	flat_store_dwordx4 v[118:119], v[114:117]
	s_cbranch_vccnz .LBB0_1066
	s_nop 0
	v_lshl_add_u64 v[114:115], v[188:189], 0, v[224:225]
	v_ashrrev_i32_e32 v207, 31, v206
	global_load_dwordx4 v[142:145], v[114:115], off offset:16 nt
	global_load_dwordx4 v[138:141], v[114:115], off nt
	v_lshlrev_b64 v[114:115], 13, v[206:207]
	v_lshl_add_u64 v[114:115], v[188:189], 0, v[114:115]
	v_ashrrev_i32_e32 v205, 31, v204
	global_load_dwordx4 v[134:137], v[114:115], off offset:16 nt
	global_load_dwordx4 v[130:133], v[114:115], off nt
	v_lshlrev_b64 v[114:115], 13, v[204:205]
	v_lshl_add_u64 v[114:115], v[188:189], 0, v[114:115]
	v_ashrrev_i32_e32 v203, 31, v202
	global_load_dwordx4 v[126:129], v[114:115], off offset:16 nt
	global_load_dwordx4 v[122:125], v[114:115], off nt
	v_lshlrev_b64 v[114:115], 13, v[202:203]
	v_lshl_add_u64 v[114:115], v[188:189], 0, v[114:115]
	global_load_dwordx4 v[118:121], v[114:115], off offset:16 nt
	s_nop 0
	global_load_dwordx4 v[114:117], v[114:115], off nt
	v_lshlrev_b64 v[232:233], 12, v[152:153]
	s_cbranch_execnz .LBB0_1061
.LBB0_1060:
	v_ashrrev_i32_e32 v205, 31, v204
	s_waitcnt vmcnt(0)
	global_load_dwordx4 v[228:231], v[186:187], off
	global_load_dwordx2 v[234:235], v[186:187], off offset:16
	global_load_dwordx2 v[246:247], v[186:187], off offset:24
	v_lshlrev_b64 v[122:123], 12, v[204:205]
	v_ashrrev_i32_e32 v207, 31, v206
	v_lshl_add_u64 v[122:123], v[226:227], 0, v[122:123]
	v_ashrrev_i32_e32 v203, 31, v202
	v_lshlrev_b64 v[118:119], 12, v[206:207]
	flat_load_dwordx4 v[126:129], v[122:123] nt
	v_lshlrev_b64 v[122:123], 12, v[202:203]
	v_lshl_add_u64 v[114:115], v[226:227], 0, v[232:233]
	v_lshl_add_u64 v[118:119], v[226:227], 0, v[118:119]
	v_lshl_add_u64 v[122:123], v[226:227], 0, v[122:123]
	flat_load_dwordx4 v[114:117], v[114:115] nt
	flat_load_dwordx4 v[118:121], v[118:119] nt
	flat_load_dwordx4 v[182:185], v[122:123] nt
	s_waitcnt vmcnt(0) lgkmcnt(0)
	v_lshlrev_b32_e32 v124, 16, v127
	v_and_b32_e32 v125, 0xffff0000, v127
	v_lshlrev_b32_e32 v122, 16, v126
	v_lshlrev_b32_e32 v138, 16, v114
	v_and_b32_e32 v139, 0xffff0000, v114
	v_lshlrev_b32_e32 v140, 16, v115
	v_and_b32_e32 v141, 0xffff0000, v115
	v_lshlrev_b32_e32 v142, 16, v116
	v_and_b32_e32 v143, 0xffff0000, v116
	v_lshlrev_b32_e32 v144, 16, v117
	v_and_b32_e32 v145, 0xffff0000, v117
	v_and_b32_e32 v123, 0xffff0000, v126
	v_lshlrev_b32_e32 v126, 16, v128
	v_and_b32_e32 v127, 0xffff0000, v128
	v_lshlrev_b32_e32 v128, 16, v129
	v_and_b32_e32 v129, 0xffff0000, v129
	s_waitcnt vmcnt(0) lgkmcnt(0)
	v_lshlrev_b32_e32 v130, 16, v118
	v_and_b32_e32 v131, 0xffff0000, v118
	v_lshlrev_b32_e32 v132, 16, v119
	v_and_b32_e32 v133, 0xffff0000, v119
	v_lshlrev_b32_e32 v134, 16, v120
	v_and_b32_e32 v135, 0xffff0000, v120
	v_lshlrev_b32_e32 v136, 16, v121
	v_and_b32_e32 v137, 0xffff0000, v121
	v_lshlrev_b32_e32 v114, 16, v182
	v_and_b32_e32 v115, 0xffff0000, v182
	v_lshlrev_b32_e32 v116, 16, v183
	v_and_b32_e32 v117, 0xffff0000, v183
	v_lshlrev_b32_e32 v118, 16, v184
	v_and_b32_e32 v119, 0xffff0000, v184
	v_lshlrev_b32_e32 v120, 16, v185
	v_and_b32_e32 v121, 0xffff0000, v185
	s_cmp_lt_u32 s68, 2
	s_cbranch_scc1 .Lxr2_1
	v_rcp_f32_e32 v228, v228
	v_rcp_f32_e32 v229, v229
	v_rcp_f32_e32 v230, v230
	v_rcp_f32_e32 v231, v231
	v_rcp_f32_e32 v234, v234
	v_rcp_f32_e32 v235, v235
	v_rcp_f32_e32 v246, v246
	v_rcp_f32_e32 v247, v247
	s_nop 0
	v_pk_mul_f32 v[114:115], v[114:115], v[228:229]
	v_pk_mul_f32 v[116:117], v[116:117], v[230:231]
	v_pk_mul_f32 v[118:119], v[118:119], v[234:235]
	v_pk_mul_f32 v[120:121], v[120:121], v[246:247]
	v_pk_mul_f32 v[122:123], v[122:123], v[228:229]
	v_pk_mul_f32 v[124:125], v[124:125], v[230:231]
	v_pk_mul_f32 v[126:127], v[126:127], v[234:235]
	v_pk_mul_f32 v[128:129], v[128:129], v[246:247]
	v_pk_mul_f32 v[130:131], v[130:131], v[228:229]
	v_pk_mul_f32 v[132:133], v[132:133], v[230:231]
	v_pk_mul_f32 v[134:135], v[134:135], v[234:235]
	v_pk_mul_f32 v[136:137], v[136:137], v[246:247]
	v_pk_mul_f32 v[138:139], v[138:139], v[228:229]
	v_pk_mul_f32 v[140:141], v[140:141], v[230:231]
	v_pk_mul_f32 v[142:143], v[142:143], v[234:235]
	v_pk_mul_f32 v[144:145], v[144:145], v[246:247]
.Lxr2_1:
.LBB0_1061:
	v_lshlrev_b64 v[226:227], 11, v[152:153]
	v_lshl_add_u64 v[160:161], v[226:227], 0, v[196:197]
	s_waitcnt vmcnt(0)
	v_pk_fma_f32 v[152:153], v[94:95], v[110:111], v[138:139]
	v_lshlrev_b64 v[94:95], 1, v[160:161]
	v_pk_fma_f32 v[140:141], v[96:97], v[112:113], v[140:141]
	v_pk_fma_f32 v[138:139], v[92:93], v[108:109], v[144:145]
	v_pk_fma_f32 v[144:145], v[90:91], v[106:107], v[142:143]
	v_cvt_pk_bf16_f32 v90, v152, v153
	v_cvt_pk_bf16_f32 v91, v140, v141
	v_lshl_add_u64 v[96:97], s[12:13], 0, v[94:95]
	v_cvt_pk_bf16_f32 v92, v144, v145
	v_cvt_pk_bf16_f32 v93, v138, v139
	v_lshl_add_u64 v[94:95], s[18:19], 0, v[94:95]
	v_lshlrev_b64 v[228:229], 11, v[206:207]
	v_pk_mul_f32 v[90:91], v[102:103], v[152:153]
	v_pk_mul_f32 v[92:93], v[104:105], v[140:141]
	v_cvt_pk_bf16_f32 v90, v90, v91
	v_pk_mul_f32 v[96:97], v[100:101], v[138:139]
	v_cvt_pk_bf16_f32 v91, v92, v93
	v_pk_mul_f32 v[142:143], v[98:99], v[144:145]
	v_pk_fma_f32 v[160:161], v[86:87], v[110:111], v[130:131]
	v_cvt_pk_bf16_f32 v92, v142, v143
	v_cvt_pk_bf16_f32 v93, v96, v97
	flat_store_dwordx4 v[94:95], v[90:93]
	v_pk_fma_f32 v[142:143], v[88:89], v[112:113], v[132:133]
	v_pk_fma_f32 v[134:135], v[82:83], v[106:107], v[134:135]
	v_lshl_add_u64 v[90:91], v[228:229], 0, v[196:197]
	v_lshlrev_b64 v[86:87], 1, v[90:91]
	v_cvt_pk_bf16_f32 v82, v160, v161
	v_cvt_pk_bf16_f32 v83, v142, v143
	v_lshl_add_u64 v[88:89], s[12:13], 0, v[86:87]
	v_pk_fma_f32 v[136:137], v[84:85], v[108:109], v[136:137]
	v_cvt_pk_bf16_f32 v84, v134, v135
	v_lshl_add_u64 v[86:87], s[18:19], 0, v[86:87]
	v_cvt_pk_bf16_f32 v85, v136, v137
	v_lshlrev_b64 v[230:231], 11, v[204:205]
	v_pk_mul_f32 v[88:89], v[100:101], v[136:137]
	v_pk_mul_f32 v[82:83], v[102:103], v[160:161]
	v_pk_mul_f32 v[84:85], v[104:105], v[142:143]
	v_cvt_pk_bf16_f32 v82, v82, v83
	v_pk_mul_f32 v[90:91], v[98:99], v[134:135]
	v_cvt_pk_bf16_f32 v83, v84, v85
	v_pk_fma_f32 v[132:133], v[78:79], v[110:111], v[122:123]
	v_cvt_pk_bf16_f32 v84, v90, v91
	v_cvt_pk_bf16_f32 v85, v88, v89
	flat_store_dwordx4 v[86:87], v[82:85]
	v_pk_fma_f32 v[130:131], v[80:81], v[112:113], v[124:125]
	v_pk_fma_f32 v[126:127], v[74:75], v[106:107], v[126:127]
	v_lshl_add_u64 v[82:83], v[230:231], 0, v[196:197]
	v_lshlrev_b64 v[78:79], 1, v[82:83]
	v_cvt_pk_bf16_f32 v74, v132, v133
	v_cvt_pk_bf16_f32 v75, v130, v131
	v_lshl_add_u64 v[80:81], s[12:13], 0, v[78:79]
	v_pk_fma_f32 v[124:125], v[76:77], v[108:109], v[128:129]
	v_cvt_pk_bf16_f32 v76, v126, v127
	v_lshl_add_u64 v[78:79], s[18:19], 0, v[78:79]
	v_cvt_pk_bf16_f32 v77, v124, v125
	v_lshlrev_b64 v[128:129], 11, v[202:203]
	v_pk_mul_f32 v[80:81], v[100:101], v[124:125]
	v_pk_mul_f32 v[74:75], v[102:103], v[132:133]
	v_pk_mul_f32 v[76:77], v[104:105], v[130:131]
	v_cvt_pk_bf16_f32 v74, v74, v75
	v_pk_mul_f32 v[82:83], v[98:99], v[126:127]
	v_cvt_pk_bf16_f32 v75, v76, v77
	v_pk_fma_f32 v[122:123], v[70:71], v[110:111], v[114:115]
	v_cvt_pk_bf16_f32 v76, v82, v83
	v_cvt_pk_bf16_f32 v77, v80, v81
	flat_store_dwordx4 v[78:79], v[74:77]
	v_pk_fma_f32 v[116:117], v[72:73], v[112:113], v[116:117]
	v_pk_fma_f32 v[114:115], v[68:69], v[108:109], v[120:121]
	v_lshl_add_u64 v[74:75], v[128:129], 0, v[196:197]
	v_lshlrev_b64 v[70:71], 1, v[74:75]
	v_pk_fma_f32 v[118:119], v[66:67], v[106:107], v[118:119]
	v_cvt_pk_bf16_f32 v66, v122, v123
	v_cvt_pk_bf16_f32 v67, v116, v117
	v_lshl_add_u64 v[72:73], s[12:13], 0, v[70:71]
	v_cvt_pk_bf16_f32 v68, v118, v119
	v_cvt_pk_bf16_f32 v69, v114, v115
	v_lshl_add_u64 v[70:71], s[18:19], 0, v[70:71]
	v_pk_mul_f32 v[72:73], v[100:101], v[114:115]
	v_pk_mul_f32 v[68:69], v[104:105], v[116:117]
	v_pk_mul_f32 v[66:67], v[102:103], v[122:123]
	v_pk_mul_f32 v[74:75], v[98:99], v[118:119]
	v_cvt_pk_bf16_f32 v66, v66, v67
	v_cvt_pk_bf16_f32 v67, v68, v69
	s_and_b64 vcc, exec, s[8:9]
	v_cvt_pk_bf16_f32 v68, v74, v75
	v_cvt_pk_bf16_f32 v69, v72, v73
	flat_store_dwordx4 v[70:71], v[66:69]
	flat_load_dwordx4 v[78:81], v[208:209] offset:512
	flat_load_dwordx4 v[74:77], v[208:209] offset:528
	s_nop 0
	flat_load_dwordx4 v[70:73], v[210:211] offset:512
	flat_load_dwordx4 v[66:69], v[210:211] offset:528
	s_cbranch_vccnz .LBB0_1067
	v_lshl_add_u64 v[82:83], v[188:189], 0, v[212:213]
	global_load_dwordx4 v[110:113], v[82:83], off offset:528 nt
	global_load_dwordx4 v[106:109], v[82:83], off offset:512 nt
	v_lshlrev_b64 v[82:83], 13, v[200:201]
	v_lshl_add_u64 v[82:83], v[188:189], 0, v[82:83]
	global_load_dwordx4 v[102:105], v[82:83], off offset:528 nt
	global_load_dwordx4 v[98:101], v[82:83], off offset:512 nt
	v_lshlrev_b64 v[82:83], 13, v[198:199]
	v_lshl_add_u64 v[82:83], v[188:189], 0, v[82:83]
	global_load_dwordx4 v[94:97], v[82:83], off offset:528 nt
	global_load_dwordx4 v[90:93], v[82:83], off offset:512 nt
	v_lshlrev_b64 v[82:83], 13, v[194:195]
	v_lshl_add_u64 v[82:83], v[188:189], 0, v[82:83]
	global_load_dwordx4 v[86:89], v[82:83], off offset:528 nt
	s_nop 0
	global_load_dwordx4 v[82:85], v[82:83], off offset:512 nt
	s_mov_b64 s[30:31], 0
	s_branch .LBB0_1068

.LBB0_1068:
	v_or_b32_e32 v120, 0x80, v196
	v_ashrrev_i32_e32 v121, 31, v120
	s_andn2_b64 vcc, exec, s[30:31]
	v_lshlrev_b64 v[196:197], 1, v[120:121]
	s_cbranch_vccnz .LBB0_1070
	s_waitcnt vmcnt(0)
	global_load_dwordx4 v[208:211], v[186:187], off offset:512
	global_load_dwordx2 v[212:213], v[186:187], off offset:528
	global_load_dwordx2 v[234:235], v[186:187], off offset:536
	v_lshlrev_b64 v[90:91], 12, v[198:199]
	v_lshl_add_u64 v[90:91], s[12:13], 0, v[90:91]
	v_lshl_add_u64 v[90:91], v[90:91], 0, v[196:197]
	v_lshlrev_b64 v[86:87], 12, v[200:201]
	flat_load_dwordx4 v[94:97], v[90:91] nt
	v_lshlrev_b64 v[90:91], 12, v[194:195]
	v_lshl_add_u64 v[82:83], s[12:13], 0, v[214:215]
	v_lshl_add_u64 v[86:87], s[12:13], 0, v[86:87]
	v_lshl_add_u64 v[90:91], s[12:13], 0, v[90:91]
	v_lshl_add_u64 v[82:83], v[82:83], 0, v[196:197]
	v_lshl_add_u64 v[86:87], v[86:87], 0, v[196:197]
	v_lshl_add_u64 v[90:91], v[90:91], 0, v[196:197]
	flat_load_dwordx4 v[82:85], v[82:83] nt
	flat_load_dwordx4 v[86:89], v[86:87] nt
	flat_load_dwordx4 v[182:185], v[90:91] nt
	s_waitcnt vmcnt(0) lgkmcnt(0)
	v_lshlrev_b32_e32 v92, 16, v95
	v_and_b32_e32 v93, 0xffff0000, v95
	v_lshlrev_b32_e32 v90, 16, v94
	v_and_b32_e32 v91, 0xffff0000, v94
	v_lshlrev_b32_e32 v94, 16, v96
	v_and_b32_e32 v95, 0xffff0000, v96
	v_lshlrev_b32_e32 v106, 16, v82
	v_and_b32_e32 v107, 0xffff0000, v82
	v_lshlrev_b32_e32 v108, 16, v83
	v_and_b32_e32 v109, 0xffff0000, v83
	v_lshlrev_b32_e32 v110, 16, v84
	v_and_b32_e32 v111, 0xffff0000, v84
	v_lshlrev_b32_e32 v112, 16, v85
	v_and_b32_e32 v113, 0xffff0000, v85
	v_lshlrev_b32_e32 v96, 16, v97
	v_and_b32_e32 v97, 0xffff0000, v97
	s_waitcnt vmcnt(0) lgkmcnt(0)
	v_lshlrev_b32_e32 v98, 16, v86
	v_and_b32_e32 v99, 0xffff0000, v86
	v_lshlrev_b32_e32 v100, 16, v87
	v_and_b32_e32 v101, 0xffff0000, v87
	v_lshlrev_b32_e32 v102, 16, v88
	v_and_b32_e32 v103, 0xffff0000, v88
	v_lshlrev_b32_e32 v104, 16, v89
	v_and_b32_e32 v105, 0xffff0000, v89
	v_lshlrev_b32_e32 v82, 16, v182
	v_and_b32_e32 v83, 0xffff0000, v182
	v_lshlrev_b32_e32 v84, 16, v183
	v_and_b32_e32 v85, 0xffff0000, v183
	v_lshlrev_b32_e32 v86, 16, v184
	v_and_b32_e32 v87, 0xffff0000, v184
	v_lshlrev_b32_e32 v88, 16, v185
	v_and_b32_e32 v89, 0xffff0000, v185
	s_cmp_lt_u32 s68, 2
	s_cbranch_scc1 .Lxr2_2
	v_rcp_f32_e32 v208, v208
	v_rcp_f32_e32 v209, v209
	v_rcp_f32_e32 v210, v210
	v_rcp_f32_e32 v211, v211
	v_rcp_f32_e32 v212, v212
	v_rcp_f32_e32 v213, v213
	v_rcp_f32_e32 v234, v234
	v_rcp_f32_e32 v235, v235
	s_nop 0
	v_pk_mul_f32 v[82:83], v[82:83], v[208:209]
	v_pk_mul_f32 v[84:85], v[84:85], v[210:211]
	v_pk_mul_f32 v[86:87], v[86:87], v[212:213]
	v_pk_mul_f32 v[88:89], v[88:89], v[234:235]
	v_pk_mul_f32 v[90:91], v[90:91], v[208:209]
	v_pk_mul_f32 v[92:93], v[92:93], v[210:211]
	v_pk_mul_f32 v[94:95], v[94:95], v[212:213]
	v_pk_mul_f32 v[96:97], v[96:97], v[234:235]
	v_pk_mul_f32 v[98:99], v[98:99], v[208:209]
	v_pk_mul_f32 v[100:101], v[100:101], v[210:211]
	v_pk_mul_f32 v[102:103], v[102:103], v[212:213]
	v_pk_mul_f32 v[104:105], v[104:105], v[234:235]
	v_pk_mul_f32 v[106:107], v[106:107], v[208:209]
	v_pk_mul_f32 v[108:109], v[108:109], v[210:211]
	v_pk_mul_f32 v[110:111], v[110:111], v[212:213]
	v_pk_mul_f32 v[112:113], v[112:113], v[234:235]
.Lxr2_2:
.LBB0_1070:
	v_lshl_add_u64 v[182:183], v[216:217], 0, v[120:121]
	s_waitcnt vmcnt(0) lgkmcnt(0)
	v_pk_fma_f32 v[198:199], v[62:63], v[78:79], v[106:107]
	v_lshlrev_b64 v[62:63], 1, v[182:183]
	v_pk_fma_f32 v[194:195], v[64:65], v[80:81], v[108:109]
	v_pk_fma_f32 v[110:111], v[58:59], v[74:75], v[110:111]
	v_cvt_pk_bf16_f32 v58, v198, v199
	v_cvt_pk_bf16_f32 v59, v194, v195
	v_lshl_add_u64 v[64:65], s[12:13], 0, v[62:63]
	v_pk_fma_f32 v[112:113], v[60:61], v[76:77], v[112:113]
	v_cvt_pk_bf16_f32 v60, v110, v111
	v_lshl_add_u64 v[62:63], s[18:19], 0, v[62:63]
	v_cvt_pk_bf16_f32 v61, v112, v113
	v_pk_mul_f32 v[64:65], v[68:69], v[112:113]
	v_pk_mul_f32 v[106:107], v[66:67], v[110:111]
	v_pk_mul_f32 v[58:59], v[70:71], v[198:199]
	v_pk_mul_f32 v[60:61], v[72:73], v[194:195]
	v_cvt_pk_bf16_f32 v58, v58, v59
	v_pk_fma_f32 v[108:109], v[54:55], v[78:79], v[98:99]
	v_cvt_pk_bf16_f32 v59, v60, v61
	v_cvt_pk_bf16_f32 v60, v106, v107
	v_cvt_pk_bf16_f32 v61, v64, v65
	flat_store_dwordx4 v[62:63], v[58:61]
	v_pk_fma_f32 v[106:107], v[56:57], v[80:81], v[100:101]
	v_pk_fma_f32 v[102:103], v[50:51], v[74:75], v[102:103]
	v_lshl_add_u64 v[58:59], v[218:219], 0, v[120:121]
	v_lshlrev_b64 v[54:55], 1, v[58:59]
	v_cvt_pk_bf16_f32 v50, v108, v109
	v_cvt_pk_bf16_f32 v51, v106, v107
	v_lshl_add_u64 v[56:57], s[12:13], 0, v[54:55]
	v_pk_fma_f32 v[104:105], v[52:53], v[76:77], v[104:105]
	v_cvt_pk_bf16_f32 v52, v102, v103
	v_lshl_add_u64 v[54:55], s[18:19], 0, v[54:55]
	v_cvt_pk_bf16_f32 v53, v104, v105
	v_pk_mul_f32 v[56:57], v[68:69], v[104:105]
	v_pk_mul_f32 v[58:59], v[66:67], v[102:103]
	v_pk_mul_f32 v[50:51], v[70:71], v[108:109]
	v_pk_mul_f32 v[52:53], v[72:73], v[106:107]
	v_cvt_pk_bf16_f32 v50, v50, v51
	v_pk_fma_f32 v[100:101], v[46:47], v[78:79], v[90:91]
	v_cvt_pk_bf16_f32 v51, v52, v53
	v_cvt_pk_bf16_f32 v52, v58, v59
	v_cvt_pk_bf16_f32 v53, v56, v57
	flat_store_dwordx4 v[54:55], v[50:53]
	v_pk_fma_f32 v[98:99], v[48:49], v[80:81], v[92:93]
	v_pk_fma_f32 v[94:95], v[42:43], v[74:75], v[94:95]
	v_lshl_add_u64 v[50:51], v[220:221], 0, v[120:121]
	v_lshlrev_b64 v[46:47], 1, v[50:51]
	v_cvt_pk_bf16_f32 v42, v100, v101
	v_cvt_pk_bf16_f32 v43, v98, v99
	v_lshl_add_u64 v[48:49], s[12:13], 0, v[46:47]
	v_pk_fma_f32 v[92:93], v[44:45], v[76:77], v[96:97]
	v_cvt_pk_bf16_f32 v44, v94, v95
	v_lshl_add_u64 v[46:47], s[18:19], 0, v[46:47]
	v_cvt_pk_bf16_f32 v45, v92, v93
	v_pk_mul_f32 v[48:49], v[68:69], v[92:93]
	v_pk_mul_f32 v[50:51], v[66:67], v[94:95]
	v_pk_mul_f32 v[42:43], v[70:71], v[100:101]
	v_pk_mul_f32 v[44:45], v[72:73], v[98:99]
	v_cvt_pk_bf16_f32 v42, v42, v43
	v_pk_fma_f32 v[90:91], v[38:39], v[78:79], v[82:83]
	v_cvt_pk_bf16_f32 v43, v44, v45
	v_cvt_pk_bf16_f32 v44, v50, v51
	v_cvt_pk_bf16_f32 v45, v48, v49
	flat_store_dwordx4 v[46:47], v[42:45]
	v_pk_fma_f32 v[84:85], v[40:41], v[80:81], v[84:85]
	v_pk_fma_f32 v[82:83], v[36:37], v[76:77], v[88:89]
	v_lshl_add_u64 v[42:43], v[222:223], 0, v[120:121]
	v_lshlrev_b64 v[38:39], 1, v[42:43]
	v_pk_fma_f32 v[86:87], v[34:35], v[74:75], v[86:87]
	v_cvt_pk_bf16_f32 v34, v90, v91
	v_cvt_pk_bf16_f32 v35, v84, v85
	v_lshl_add_u64 v[40:41], s[12:13], 0, v[38:39]
	v_cvt_pk_bf16_f32 v36, v86, v87
	v_cvt_pk_bf16_f32 v37, v82, v83
	v_lshl_add_u64 v[38:39], s[18:19], 0, v[38:39]
	s_and_b64 vcc, exec, s[8:9]
	v_pk_mul_f32 v[36:37], v[72:73], v[84:85]
	v_pk_mul_f32 v[34:35], v[70:71], v[90:91]
	v_pk_mul_f32 v[40:41], v[68:69], v[82:83]
	v_pk_mul_f32 v[42:43], v[66:67], v[86:87]
	v_cvt_pk_bf16_f32 v34, v34, v35
	v_cvt_pk_bf16_f32 v35, v36, v37
	s_nop 0
	v_cvt_pk_bf16_f32 v36, v42, v43
	v_cvt_pk_bf16_f32 v37, v40, v41
	flat_store_dwordx4 v[38:39], v[34:37]
	s_cbranch_vccnz .LBB0_1092
	s_nop 0
	v_lshl_add_u64 v[34:35], v[188:189], 0, v[224:225]
	global_load_dwordx4 v[62:65], v[34:35], off offset:528 nt
	global_load_dwordx4 v[58:61], v[34:35], off offset:512 nt
	v_lshlrev_b64 v[34:35], 13, v[206:207]
	v_lshl_add_u64 v[34:35], v[188:189], 0, v[34:35]
	global_load_dwordx4 v[54:57], v[34:35], off offset:528 nt
	global_load_dwordx4 v[50:53], v[34:35], off offset:512 nt
	v_lshlrev_b64 v[34:35], 13, v[204:205]
	v_lshl_add_u64 v[34:35], v[188:189], 0, v[34:35]
	global_load_dwordx4 v[46:49], v[34:35], off offset:528 nt
	global_load_dwordx4 v[42:45], v[34:35], off offset:512 nt
	v_lshlrev_b64 v[34:35], 13, v[202:203]
	v_lshl_add_u64 v[34:35], v[188:189], 0, v[34:35]
	global_load_dwordx4 v[38:41], v[34:35], off offset:528 nt
	s_nop 0
	global_load_dwordx4 v[34:37], v[34:35], off offset:512 nt
	s_cbranch_execnz .LBB0_1073
.LBB0_1072:
	s_waitcnt vmcnt(0)
	global_load_dwordx4 v[208:211], v[186:187], off offset:512
	global_load_dwordx4 v[212:215], v[186:187], off offset:528
	v_lshlrev_b64 v[42:43], 12, v[204:205]
	v_lshl_add_u64 v[42:43], s[12:13], 0, v[42:43]
	v_lshl_add_u64 v[42:43], v[42:43], 0, v[196:197]
	v_lshlrev_b64 v[38:39], 12, v[206:207]
	flat_load_dwordx4 v[46:49], v[42:43] nt
	v_lshlrev_b64 v[42:43], 12, v[202:203]
	v_lshl_add_u64 v[34:35], s[12:13], 0, v[232:233]
	v_lshl_add_u64 v[38:39], s[12:13], 0, v[38:39]
	v_lshl_add_u64 v[42:43], s[12:13], 0, v[42:43]
	v_lshl_add_u64 v[34:35], v[34:35], 0, v[196:197]
	v_lshl_add_u64 v[38:39], v[38:39], 0, v[196:197]
	v_lshl_add_u64 v[42:43], v[42:43], 0, v[196:197]
	flat_load_dwordx4 v[34:37], v[34:35] nt
	flat_load_dwordx4 v[38:41], v[38:39] nt
	flat_load_dwordx4 v[182:185], v[42:43] nt
	s_waitcnt vmcnt(0) lgkmcnt(0)
	v_lshlrev_b32_e32 v44, 16, v47
	v_and_b32_e32 v45, 0xffff0000, v47
	v_lshlrev_b32_e32 v42, 16, v46
	v_and_b32_e32 v43, 0xffff0000, v46
	v_lshlrev_b32_e32 v46, 16, v48
	v_and_b32_e32 v47, 0xffff0000, v48
	v_lshlrev_b32_e32 v58, 16, v34
	v_and_b32_e32 v59, 0xffff0000, v34
	v_lshlrev_b32_e32 v60, 16, v35
	v_and_b32_e32 v61, 0xffff0000, v35
	v_lshlrev_b32_e32 v62, 16, v36
	v_and_b32_e32 v63, 0xffff0000, v36
	v_lshlrev_b32_e32 v64, 16, v37
	v_and_b32_e32 v65, 0xffff0000, v37
	v_lshlrev_b32_e32 v48, 16, v49
	v_and_b32_e32 v49, 0xffff0000, v49
	s_waitcnt vmcnt(0) lgkmcnt(0)
	v_lshlrev_b32_e32 v50, 16, v38
	v_and_b32_e32 v51, 0xffff0000, v38
	v_lshlrev_b32_e32 v52, 16, v39
	v_and_b32_e32 v53, 0xffff0000, v39
	v_lshlrev_b32_e32 v54, 16, v40
	v_and_b32_e32 v55, 0xffff0000, v40
	v_lshlrev_b32_e32 v56, 16, v41
	v_and_b32_e32 v57, 0xffff0000, v41
	v_lshlrev_b32_e32 v34, 16, v182
	v_and_b32_e32 v35, 0xffff0000, v182
	v_lshlrev_b32_e32 v36, 16, v183
	v_and_b32_e32 v37, 0xffff0000, v183
	v_lshlrev_b32_e32 v38, 16, v184
	v_and_b32_e32 v39, 0xffff0000, v184
	v_lshlrev_b32_e32 v40, 16, v185
	v_and_b32_e32 v41, 0xffff0000, v185
	s_cmp_lt_u32 s68, 2
	s_cbranch_scc1 .Lxr2_3
	v_rcp_f32_e32 v208, v208
	v_rcp_f32_e32 v209, v209
	v_rcp_f32_e32 v210, v210
	v_rcp_f32_e32 v211, v211
	v_rcp_f32_e32 v212, v212
	v_rcp_f32_e32 v213, v213
	v_rcp_f32_e32 v214, v214
	v_rcp_f32_e32 v215, v215
	s_nop 0
	v_pk_mul_f32 v[34:35], v[34:35], v[208:209]
	v_pk_mul_f32 v[36:37], v[36:37], v[210:211]
	v_pk_mul_f32 v[38:39], v[38:39], v[212:213]
	v_pk_mul_f32 v[40:41], v[40:41], v[214:215]
	v_pk_mul_f32 v[42:43], v[42:43], v[208:209]
	v_pk_mul_f32 v[44:45], v[44:45], v[210:211]
	v_pk_mul_f32 v[46:47], v[46:47], v[212:213]
	v_pk_mul_f32 v[48:49], v[48:49], v[214:215]
	v_pk_mul_f32 v[50:51], v[50:51], v[208:209]
	v_pk_mul_f32 v[52:53], v[52:53], v[210:211]
	v_pk_mul_f32 v[54:55], v[54:55], v[212:213]
	v_pk_mul_f32 v[56:57], v[56:57], v[214:215]
	v_pk_mul_f32 v[58:59], v[58:59], v[208:209]
	v_pk_mul_f32 v[60:61], v[60:61], v[210:211]
	v_pk_mul_f32 v[62:63], v[62:63], v[212:213]
	v_pk_mul_f32 v[64:65], v[64:65], v[214:215]

.LBB0_1240:
	s_lshl_b32 s1, s1, 8
	s_add_i32 s1, s1, s72
	v_and_or_b32 v166, v156, 15, s1
	v_ashrrev_i32_e32 v177, 31, v176
	v_ashrrev_i32_e32 v167, 31, v166
	v_lshl_add_u64 v[170:171], v[176:177], 1, s[12:13]
	v_lshlrev_b64 v[188:189], 12, v[166:167]
	v_lshl_add_u64 v[186:187], v[170:171], 0, v[188:189]
	v_or_b32_e32 v198, 16, v166
	v_or_b32_e32 v200, 32, v166
	v_or_b32_e32 v174, 48, v166
	v_lshl_add_u64 v[246:247], v[186:187], 0, s[98:99]
	flat_load_dwordx4 v[182:185], v[246:247] nt
	v_ashrrev_i32_e32 v199, 31, v198
	v_ashrrev_i32_e32 v201, 31, v200
	v_ashrrev_i32_e32 v175, 31, v174
	v_lshlrev_b64 v[190:191], 12, v[198:199]
	v_lshlrev_b64 v[192:193], 12, v[200:201]
	v_lshlrev_b64 v[194:195], 12, v[174:175]
	v_lshl_add_u64 v[204:205], v[170:171], 0, v[190:191]
	v_lshl_add_u64 v[202:203], v[170:171], 0, v[192:193]
	v_lshl_add_u64 v[172:173], v[170:171], 0, v[194:195]
	v_lshl_add_u64 v[246:247], v[204:205], 0, s[98:99]
	flat_load_dwordx4 v[162:165], v[246:247] nt
	v_lshl_add_u64 v[246:247], v[202:203], 0, s[98:99]
	flat_load_dwordx4 v[158:161], v[246:247] nt
	v_lshl_add_u64 v[246:247], v[172:173], 0, s[98:99]
	flat_load_dwordx4 v[154:157], v[246:247] nt
	v_lshlrev_b64 v[196:197], 11, v[166:167]
	v_lshl_add_u64 v[206:207], v[196:197], 0, v[176:177]
	s_andn2_b64 vcc, exec, s[10:11]
	s_waitcnt vmcnt(0) lgkmcnt(0)
	v_rcp_f32_e32 v232, v232
	v_rcp_f32_e32 v233, v233
	v_rcp_f32_e32 v234, v234
	v_rcp_f32_e32 v235, v235
	v_rcp_f32_e32 v240, v240
	v_rcp_f32_e32 v241, v241
	v_rcp_f32_e32 v242, v242
	v_rcp_f32_e32 v243, v243
	s_nop 0
	v_lshlrev_b32_e32 v168, 16, v182
	v_and_b32_e32 v169, 0xffff0000, v182
	v_lshlrev_b32_e32 v208, 16, v184
	v_and_b32_e32 v209, 0xffff0000, v184
	v_lshlrev_b32_e32 v184, 16, v185
	v_and_b32_e32 v185, 0xffff0000, v185
	v_lshlrev_b32_e32 v182, 16, v183
	v_and_b32_e32 v183, 0xffff0000, v183
	v_pk_mul_f32 v[168:169], v[168:169], v[232:233]
	v_pk_fma_f32 v[168:169], v[150:151], v[110:111], v[168:169]
	v_pk_mul_f32 v[208:209], v[208:209], v[240:241]
	v_pk_fma_f32 v[150:151], v[146:147], v[106:107], v[208:209]
	v_pk_mul_f32 v[184:185], v[184:185], v[242:243]
	v_pk_fma_f32 v[146:147], v[148:149], v[108:109], v[184:185]
	v_cndmask_b32_e64 v148, 0, 1, s[10:11]
	v_pk_mul_f32 v[182:183], v[182:183], v[234:235]
	v_pk_fma_f32 v[152:153], v[152:153], v[112:113], v[182:183]
	v_cmp_ne_u32_e64 s[8:9], 1, v148
	v_cvt_pk_bf16_f32 v182, v168, v169
	v_cvt_pk_bf16_f32 v183, v152, v153
	v_cvt_pk_bf16_f32 v184, v150, v151
	v_cvt_pk_bf16_f32 v185, v146, v147
	s_cbranch_vccz .Lxs2_1
	flat_store_dwordx4 v[186:187], v[182:185]

.LBB0_1256:
	v_add_u32_e32 v186, 0x80, v166
	v_ashrrev_i32_e32 v187, 31, v186
	v_lshlrev_b64 v[204:205], 12, v[186:187]
	v_add_u32_e32 v164, 0x90, v166
	v_add_u32_e32 v172, 0xa0, v166
	v_add_u32_e32 v220, 0xb0, v166
	v_lshl_add_u64 v[214:215], v[170:171], 0, v[204:205]
	v_ashrrev_i32_e32 v165, 31, v164
	v_ashrrev_i32_e32 v173, 31, v172
	v_ashrrev_i32_e32 v221, 31, v220
	v_lshl_add_u64 v[246:247], v[214:215], 0, s[98:99]
	flat_load_dwordx4 v[182:185], v[246:247] nt
	v_lshlrev_b64 v[206:207], 12, v[164:165]
	v_lshlrev_b64 v[208:209], 12, v[172:173]
	v_lshlrev_b64 v[210:211], 12, v[220:221]
	v_lshl_add_u64 v[174:175], v[170:171], 0, v[206:207]
	v_lshl_add_u64 v[222:223], v[170:171], 0, v[208:209]
	v_lshl_add_u64 v[218:219], v[170:171], 0, v[210:211]
	v_lshl_add_u64 v[246:247], v[174:175], 0, s[98:99]
	flat_load_dwordx4 v[130:133], v[246:247] nt
	v_lshl_add_u64 v[246:247], v[222:223], 0, s[98:99]
	flat_load_dwordx4 v[126:129], v[246:247] nt
	v_lshl_add_u64 v[246:247], v[218:219], 0, s[98:99]
	flat_load_dwordx4 v[122:125], v[246:247] nt
	v_lshlrev_b64 v[212:213], 11, v[186:187]
	v_lshl_add_u64 v[170:171], v[212:213], 0, v[176:177]
	s_and_b64 vcc, exec, s[8:9]
	s_waitcnt vmcnt(0) lgkmcnt(0)
	v_lshlrev_b32_e32 v216, 16, v182
	v_and_b32_e32 v217, 0xffff0000, v182
	v_lshlrev_b32_e32 v182, 16, v183
	v_and_b32_e32 v183, 0xffff0000, v183
	v_lshlrev_b32_e32 v230, 16, v184
	v_and_b32_e32 v231, 0xffff0000, v184
	v_lshlrev_b32_e32 v184, 16, v185
	v_and_b32_e32 v185, 0xffff0000, v185
	v_pk_mul_f32 v[182:183], v[182:183], v[234:235]
	v_pk_fma_f32 v[120:121], v[120:121], v[112:113], v[182:183]
	v_pk_mul_f32 v[216:217], v[216:217], v[232:233]
	v_pk_fma_f32 v[118:119], v[118:119], v[110:111], v[216:217]
	v_pk_mul_f32 v[230:231], v[230:231], v[240:241]
	v_pk_fma_f32 v[114:115], v[114:115], v[106:107], v[230:231]
	v_pk_mul_f32 v[184:185], v[184:185], v[242:243]
	v_pk_fma_f32 v[116:117], v[116:117], v[108:109], v[184:185]
	v_cvt_pk_bf16_f32 v182, v118, v119
	v_cvt_pk_bf16_f32 v183, v120, v121
	v_cvt_pk_bf16_f32 v184, v114, v115
	s_nop 0
	v_cvt_pk_bf16_f32 v185, v116, v117
	s_cbranch_vccz .Lxs2_5
	flat_store_dwordx4 v[214:215], v[182:185]

.LBB0_1276:
	v_ashrrev_i32_e32 v103, 31, v102
	v_lshl_add_u64 v[90:91], s[12:13], 0, v[188:189]
	v_lshlrev_b64 v[104:105], 1, v[102:103]
	v_lshl_add_u64 v[186:187], v[90:91], 0, v[104:105]
	v_lshl_add_u64 v[90:91], s[12:13], 0, v[190:191]
	v_lshl_add_u64 v[246:247], v[186:187], 0, s[98:99]
	flat_load_dwordx4 v[182:185], v[246:247] nt
	v_lshl_add_u64 v[92:93], s[12:13], 0, v[192:193]
	v_lshl_add_u64 v[94:95], s[12:13], 0, v[194:195]
	v_lshl_add_u64 v[178:179], v[90:91], 0, v[104:105]
	v_lshl_add_u64 v[176:177], v[92:93], 0, v[104:105]
	v_lshl_add_u64 v[124:125], v[94:95], 0, v[104:105]
	v_lshl_add_u64 v[246:247], v[178:179], 0, s[98:99]
	flat_load_dwordx4 v[98:101], v[246:247] nt
	v_lshl_add_u64 v[246:247], v[176:177], 0, s[98:99]
	flat_load_dwordx4 v[94:97], v[246:247] nt
	v_lshl_add_u64 v[246:247], v[124:125], 0, s[98:99]
	flat_load_dwordx4 v[90:93], v[246:247] nt
	v_lshl_add_u64 v[188:189], v[196:197], 0, v[102:103]
	s_and_b64 vcc, exec, s[8:9]
	s_waitcnt vmcnt(0) lgkmcnt(0)
	v_rcp_f32_e32 v232, v232
	v_rcp_f32_e32 v233, v233
	v_rcp_f32_e32 v234, v234
	v_rcp_f32_e32 v235, v235
	v_rcp_f32_e32 v240, v240
	v_rcp_f32_e32 v241, v241
	v_rcp_f32_e32 v242, v242
	v_rcp_f32_e32 v243, v243
	s_nop 0
	v_lshlrev_b32_e32 v190, 16, v182
	v_and_b32_e32 v191, 0xffff0000, v182
	v_lshlrev_b32_e32 v182, 16, v183
	v_and_b32_e32 v183, 0xffff0000, v183
	v_lshlrev_b32_e32 v192, 16, v184
	v_and_b32_e32 v193, 0xffff0000, v184
	v_lshlrev_b32_e32 v184, 16, v185
	v_and_b32_e32 v185, 0xffff0000, v185
	v_pk_mul_f32 v[182:183], v[182:183], v[234:235]
	v_pk_fma_f32 v[64:65], v[64:65], v[88:89], v[182:183]
	v_pk_mul_f32 v[190:191], v[190:191], v[232:233]
	v_pk_fma_f32 v[62:63], v[62:63], v[86:87], v[190:191]
	v_pk_mul_f32 v[192:193], v[192:193], v[240:241]
	v_pk_fma_f32 v[58:59], v[58:59], v[82:83], v[192:193]
	v_pk_mul_f32 v[184:185], v[184:185], v[242:243]
	v_pk_fma_f32 v[60:61], v[60:61], v[84:85], v[184:185]
	v_cvt_pk_bf16_f32 v182, v62, v63
	v_cvt_pk_bf16_f32 v183, v64, v65
	v_cvt_pk_bf16_f32 v184, v58, v59
	s_nop 0
	v_cvt_pk_bf16_f32 v185, v60, v61
	s_cbranch_vccz .Lxs2_9
	flat_store_dwordx4 v[186:187], v[182:185]

.LBB0_1292:
	s_nop 1
	v_lshl_add_u64 v[34:35], s[12:13], 0, v[204:205]
	v_lshl_add_u64 v[186:187], v[34:35], 0, v[104:105]
	v_lshl_add_u64 v[34:35], s[12:13], 0, v[206:207]
	v_lshl_add_u64 v[246:247], v[186:187], 0, s[98:99]
	flat_load_dwordx4 v[182:185], v[246:247] nt
	v_lshl_add_u64 v[36:37], s[12:13], 0, v[208:209]
	v_lshl_add_u64 v[38:39], s[12:13], 0, v[210:211]
	v_lshl_add_u64 v[176:177], v[34:35], 0, v[104:105]
	v_lshl_add_u64 v[124:125], v[36:37], 0, v[104:105]
	v_lshl_add_u64 v[104:105], v[38:39], 0, v[104:105]
	v_lshl_add_u64 v[246:247], v[176:177], 0, s[98:99]
	flat_load_dwordx4 v[42:45], v[246:247] nt
	v_lshl_add_u64 v[246:247], v[124:125], 0, s[98:99]
	flat_load_dwordx4 v[38:41], v[246:247] nt
	v_lshl_add_u64 v[246:247], v[104:105], 0, s[98:99]
	flat_load_dwordx4 v[34:37], v[246:247] nt
	v_lshl_add_u64 v[178:179], v[212:213], 0, v[102:103]
	s_and_b64 vcc, exec, s[8:9]
	s_waitcnt vmcnt(0) lgkmcnt(0)
	v_lshlrev_b32_e32 v188, 16, v182
	v_and_b32_e32 v189, 0xffff0000, v182
	v_lshlrev_b32_e32 v182, 16, v183
	v_and_b32_e32 v183, 0xffff0000, v183
	v_lshlrev_b32_e32 v190, 16, v184
	v_and_b32_e32 v191, 0xffff0000, v184
	v_lshlrev_b32_e32 v184, 16, v185
	v_and_b32_e32 v185, 0xffff0000, v185
	v_pk_mul_f32 v[182:183], v[182:183], v[234:235]
	v_pk_fma_f32 v[32:33], v[32:33], v[88:89], v[182:183]
	v_pk_mul_f32 v[188:189], v[188:189], v[232:233]
	v_pk_fma_f32 v[30:31], v[30:31], v[86:87], v[188:189]
	v_pk_mul_f32 v[190:191], v[190:191], v[240:241]
	v_pk_fma_f32 v[26:27], v[26:27], v[82:83], v[190:191]
	v_pk_mul_f32 v[184:185], v[184:185], v[242:243]
	v_pk_fma_f32 v[28:29], v[28:29], v[84:85], v[184:185]
	v_cvt_pk_bf16_f32 v182, v30, v31
	v_cvt_pk_bf16_f32 v183, v32, v33
	v_cvt_pk_bf16_f32 v184, v26, v27
	s_nop 0
	v_cvt_pk_bf16_f32 v185, v28, v29
	s_cbranch_vccz .Lxs2_13
	flat_store_dwordx4 v[186:187], v[182:185]

.LBB0_1379:
	global_load_dwordx2 v[36:37], v34, s[0:1] nt
	global_load_dwordx2 v[38:39], v34, s[0:1] offset:512 nt
	global_load_dwordx2 v[40:41], v34, s[0:1] offset:1024 nt
	global_load_dwordx2 v[42:43], v34, s[0:1] offset:1536 nt
	global_load_dwordx2 v[44:45], v34, s[0:1] offset:2048 nt
	global_load_dwordx2 v[46:47], v34, s[0:1] offset:2560 nt
	global_load_dwordx2 v[48:49], v34, s[0:1] offset:3072 nt
	global_load_dwordx2 v[50:51], v34, s[0:1] offset:3584 nt
	v_lshl_add_u64 v[52:53], s[4:5], 0, v[32:33]
	v_add_co_u32_e32 v68, vcc, s8, v52
	s_add_i32 s34, s34, s36
	s_nop 0
	v_addc_co_u32_e32 v69, vcc, 0, v53, vcc
	s_add_u32 s0, s0, s2
	s_addc_u32 s1, s1, s3
	s_waitcnt vmcnt(7)
	v_lshlrev_b32_e32 v52, 16, v36
	v_and_b32_e32 v53, 0xffff0000, v36
	v_lshlrev_b32_e32 v36, 16, v37
	v_and_b32_e32 v37, 0xffff0000, v37
	s_waitcnt vmcnt(6)
	v_lshlrev_b32_e32 v54, 16, v38
	v_and_b32_e32 v55, 0xffff0000, v38
	v_lshlrev_b32_e32 v38, 16, v39
	v_and_b32_e32 v39, 0xffff0000, v39
	s_waitcnt vmcnt(5)
	v_lshlrev_b32_e32 v56, 16, v40
	v_and_b32_e32 v57, 0xffff0000, v40
	v_lshlrev_b32_e32 v40, 16, v41
	v_and_b32_e32 v41, 0xffff0000, v41
	v_mul_f32_e32 v70, v53, v53
	v_mul_f32_e32 v71, v37, v37
	v_mul_f32_e32 v72, v55, v55
	v_mul_f32_e32 v73, v39, v39
	s_waitcnt vmcnt(4)
	v_lshlrev_b32_e32 v58, 16, v42
	v_and_b32_e32 v59, 0xffff0000, v42
	v_lshlrev_b32_e32 v42, 16, v43
	v_and_b32_e32 v43, 0xffff0000, v43
	v_mul_f32_e32 v74, v57, v57
	v_mul_f32_e32 v75, v41, v41
	v_fmac_f32_e32 v70, v52, v52
	v_fmac_f32_e32 v71, v36, v36
	v_fmac_f32_e32 v72, v54, v54
	v_fmac_f32_e32 v73, v38, v38
	s_waitcnt vmcnt(3)
	v_lshlrev_b32_e32 v60, 16, v44
	v_and_b32_e32 v61, 0xffff0000, v44
	v_lshlrev_b32_e32 v44, 16, v45
	v_and_b32_e32 v45, 0xffff0000, v45
	v_mul_f32_e32 v76, v59, v59
	v_mul_f32_e32 v77, v43, v43
	v_fmac_f32_e32 v74, v56, v56
	v_fmac_f32_e32 v75, v40, v40
	v_add_f32_e32 v70, v70, v71
	v_add_f32_e32 v71, v72, v73
	s_waitcnt vmcnt(2)
	v_lshlrev_b32_e32 v62, 16, v46
	v_and_b32_e32 v63, 0xffff0000, v46
	v_lshlrev_b32_e32 v46, 16, v47
	v_and_b32_e32 v47, 0xffff0000, v47
	v_mul_f32_e32 v78, v61, v61
	v_mul_f32_e32 v79, v45, v45
	v_fmac_f32_e32 v76, v58, v58
	v_fmac_f32_e32 v77, v42, v42
	v_add_f32_e32 v72, v74, v75
	v_add_f32_e32 v70, v70, v71
	s_waitcnt vmcnt(1)
	v_lshlrev_b32_e32 v64, 16, v48
	v_and_b32_e32 v65, 0xffff0000, v48
	v_lshlrev_b32_e32 v48, 16, v49
	v_and_b32_e32 v49, 0xffff0000, v49
	v_mul_f32_e32 v80, v63, v63
	v_mul_f32_e32 v81, v47, v47
	v_fmac_f32_e32 v78, v60, v60
	v_fmac_f32_e32 v79, v44, v44
	v_add_f32_e32 v73, v76, v77
	v_add_f32_e32 v70, v70, v72
	s_waitcnt vmcnt(0)
	v_lshlrev_b32_e32 v66, 16, v50
	v_and_b32_e32 v67, 0xffff0000, v50
	v_lshlrev_b32_e32 v50, 16, v51
	v_and_b32_e32 v51, 0xffff0000, v51
	v_mul_f32_e32 v82, v65, v65
	v_mul_f32_e32 v83, v49, v49
	v_fmac_f32_e32 v80, v62, v62
	v_fmac_f32_e32 v81, v46, v46
	v_add_f32_e32 v74, v78, v79
	v_add_f32_e32 v70, v70, v73
	v_mul_f32_e32 v84, v67, v67
	v_mul_f32_e32 v85, v51, v51
	v_fmac_f32_e32 v82, v64, v64
	v_fmac_f32_e32 v83, v48, v48
	v_add_f32_e32 v75, v80, v81
	v_add_f32_e32 v70, v70, v74
	v_fmac_f32_e32 v84, v66, v66
	v_fmac_f32_e32 v85, v50, v50
	v_add_f32_e32 v76, v82, v83
	v_add_f32_e32 v70, v70, v75
	v_add_f32_e32 v77, v84, v85
	v_add_f32_e32 v70, v70, v76
	v_add_f32_e32 v70, v70, v77
	s_nop 1
	v_add_f32_dpp v70, v70, v70 quad_perm:[1,0,3,2] row_mask:0xf bank_mask:0xf bound_ctrl:1
	s_nop 1
	v_add_f32_dpp v70, v70, v70 quad_perm:[2,3,0,1] row_mask:0xf bank_mask:0xf bound_ctrl:1
	s_nop 1
	v_add_f32_dpp v70, v70, v70 row_half_mirror row_mask:0xf bank_mask:0xf bound_ctrl:1
	s_nop 1
	v_add_f32_dpp v70, v70, v70 row_mirror row_mask:0xf bank_mask:0xf bound_ctrl:1
	ds_swizzle_b32 v71, v70 offset:swizzle(SWAP,16)
	s_waitcnt lgkmcnt(0)
	v_add_f32_e32 v70, v70, v71
	v_mov_b32_e32 v71, v70
	s_nop 1
	v_permlane32_swap_b32_e32 v70, v71
	v_add_f32_e32 v70, v70, v71
	v_fmamk_f32 v70, v70, 0x3a000000, v35
	v_mul_f32_e32 v71, 0x4b800000, v70
	v_cmp_gt_f32_e32 vcc, s9, v70
	s_nop 1
	v_cndmask_b32_e32 v70, v70, v71, vcc
	v_rsq_f32_e32 v70, v70
	s_nop 0
	v_mul_f32_e32 v71, 0x45800000, v70
	v_cndmask_b32_e32 v70, v70, v71, vcc
	v_pk_mul_f32 v[52:53], v[52:53], v[70:71] op_sel_hi:[1,0]
	v_pk_mul_f32 v[36:37], v[36:37], v[70:71] op_sel_hi:[1,0]
	v_pk_mul_f32 v[54:55], v[54:55], v[70:71] op_sel_hi:[1,0]
	v_pk_mul_f32 v[72:73], v[38:39], v[70:71] op_sel_hi:[1,0]
	v_pk_mul_f32 v[56:57], v[56:57], v[70:71] op_sel_hi:[1,0]
	v_pk_mul_f32 v[74:75], v[40:41], v[70:71] op_sel_hi:[1,0]
	v_pk_mul_f32 v[58:59], v[58:59], v[70:71] op_sel_hi:[1,0]
	v_pk_mul_f32 v[76:77], v[42:43], v[70:71] op_sel_hi:[1,0]
	v_pk_mul_f32 v[60:61], v[60:61], v[70:71] op_sel_hi:[1,0]
	v_pk_mul_f32 v[78:79], v[44:45], v[70:71] op_sel_hi:[1,0]
	v_pk_mul_f32 v[62:63], v[62:63], v[70:71] op_sel_hi:[1,0]
	v_pk_mul_f32 v[80:81], v[46:47], v[70:71] op_sel_hi:[1,0]
	v_pk_mul_f32 v[64:65], v[64:65], v[70:71] op_sel_hi:[1,0]
	v_pk_mul_f32 v[82:83], v[48:49], v[70:71] op_sel_hi:[1,0]
	v_pk_mul_f32 v[38:39], v[2:3], v[36:37]
	v_pk_mul_f32 v[36:37], v[0:1], v[52:53]
	v_pk_mul_f32 v[84:85], v[66:67], v[70:71] op_sel_hi:[1,0]
	v_pk_mul_f32 v[66:67], v[50:51], v[70:71] op_sel_hi:[1,0]
	v_pk_mul_f32 v[42:43], v[6:7], v[72:73]
	v_pk_mul_f32 v[40:41], v[4:5], v[54:55]
	v_pk_mul_f32 v[46:47], v[10:11], v[74:75]
	v_pk_mul_f32 v[44:45], v[8:9], v[56:57]
	v_pk_mul_f32 v[50:51], v[14:15], v[76:77]
	v_pk_mul_f32 v[48:49], v[12:13], v[58:59]
	v_pk_mul_f32 v[54:55], v[18:19], v[78:79]
	v_pk_mul_f32 v[52:53], v[16:17], v[60:61]
	v_pk_mul_f32 v[58:59], v[22:23], v[80:81]
	v_pk_mul_f32 v[56:57], v[20:21], v[62:63]
	v_pk_mul_f32 v[62:63], v[26:27], v[82:83]
	v_pk_mul_f32 v[60:61], v[24:25], v[64:65]
	global_store_dwordx4 v32, v[36:39], s[4:5]
	global_store_dwordx4 v32, v[40:43], s[4:5] offset:1024
	global_store_dwordx4 v32, v[44:47], s[4:5] offset:2048
	global_store_dwordx4 v32, v[48:51], s[4:5] offset:3072
	global_store_dwordx4 v[68:69], v[52:55], off
	global_store_dwordx4 v[68:69], v[56:59], off offset:1024
	global_store_dwordx4 v[68:69], v[60:63], off offset:2048
	s_add_u32 s4, s4, s6
	s_addc_u32 s5, s5, s7
	v_pk_mul_f32 v[66:67], v[30:31], v[66:67]
	v_pk_mul_f32 v[64:65], v[28:29], v[84:85]
	s_cmpk_lt_i32 s34, 0x4000
	global_store_dwordx4 v[68:69], v[64:67], off offset:3072
	s_cbranch_scc1 .LBB0_1379
